# v33 + mixscan: chain (head,direction) index XOR-swizzled with the batch index so the 8 chains of a kind on one XCD read different column groups (L2 channel spread)
# speedup vs baseline: 1.0034x; 1.0033x over previous
.Lhs_mix:
	v_writelane_b32 v255, s63, 26
	v_writelane_b32 v255, s62, 27
	s_cmpk_gt_i32 s64, 0xff
	s_movk_i32 s63, 0xe00
	v_readlane_b32 s58, v255, 3
	v_readlane_b32 s72, v255, 5
	s_cbranch_scc1 .LBB0_566
	v_readlane_b32 s0, v255, 23
	s_lshl_b32 s1, s0, 5
	v_writelane_b32 v255, s1, 28
	s_lshl_b32 s1, s0, 4
	s_lshl_b32 s0, s0, 3
	s_add_u32 s82, s78, 0x8285000
	v_writelane_b32 v255, s1, 29
	s_addc_u32 s83, s79, 0
	v_writelane_b32 v255, s0, 30
	s_add_u32 s0, s78, 0x33dd000
	v_writelane_b32 v255, s0, 31
	s_addc_u32 s0, s79, 0
	s_add_u32 s84, s78, 0x3e85000
	s_addc_u32 s85, s79, 0
	s_add_u32 s86, s78, 0x3c65000
	v_writelane_b32 v255, s0, 32
	s_addc_u32 s87, s79, 0
	s_mov_b32 s65, s64
	s_lshr_b32 s0, s65, 3
	s_and_b32 s0, s0, 7
	s_xor_b32 s65, s65, s0
	s_branch .LBB0_343
